# stagger of the XCD groups halved (g x ~1.7 us)
# baseline (speedup 1.0000x reference)
; __device__ __forceinline__ void xcd_barrier(const XcdBarrier& b) {
;     ...
;     __syncthreads();
; __global__ void __launch_bounds__(NWAVES * 64, 2) fwd_kernel(Args args) {
;     ...
;         if (ph + 1 < args.ph_hi || rep + 1 < nrep) { if (args.ph_hi > 1000) grid.sync(); else xcd_barrier(xb); } else __syncthreads();
stg_loop:
	s_cmp_eq_u32 s2, 0
	s_cbranch_scc1 stg_skip
	s_sleep 63
	s_sub_u32 s2, s2, 1
	s_branch stg_loop
